# attention softmax: drop redundant max canonicalisations and 0+p add (-11 VALU per 2 tiles)
# speedup vs baseline: 1.0172x; 1.0060x over previous
.LBB0_513:
	s_lshl_b32 s4, s76, 14
	s_add_i32 s4, s4, 0
	v_add3_u32 v132, s4, v221, v220
	ds_read_b128 v[128:131], v132
	ds_read_b128 v[132:135], v132 offset:8192
	v_add3_u32 v196, s4, v222, v220
	ds_read_b128 v[192:195], v196
	ds_read_b128 v[196:199], v196 offset:8192
	s_waitcnt lgkmcnt(3)
	v_mfma_f32_32x32x16_bf16 v[144:159], v[128:131], v[160:163], 0
	s_waitcnt lgkmcnt(2)
	v_mfma_f32_32x32x16_bf16 v[128:143], v[132:135], v[160:163], 0
	s_waitcnt lgkmcnt(1)
	v_mfma_f32_32x32x16_bf16 v[144:159], v[192:195], v[164:167], v[144:159]
	s_waitcnt lgkmcnt(0)
	v_mfma_f32_32x32x16_bf16 v[128:143], v[196:199], v[164:167], v[128:143]
	v_add3_u32 v196, s4, v223, v220
	ds_read_b128 v[192:195], v196
	ds_read_b128 v[196:199], v196 offset:8192
	s_waitcnt lgkmcnt(1)
	v_mfma_f32_32x32x16_bf16 v[144:159], v[192:195], v[168:171], v[144:159]
	s_waitcnt lgkmcnt(0)
	v_mfma_f32_32x32x16_bf16 v[128:143], v[196:199], v[168:171], v[128:143]
	v_add3_u32 v196, s4, v224, v220
	ds_read_b128 v[192:195], v196
	ds_read_b128 v[196:199], v196 offset:8192
	s_waitcnt lgkmcnt(1)
	v_mfma_f32_32x32x16_bf16 v[144:159], v[192:195], v[172:175], v[144:159]
	s_waitcnt lgkmcnt(0)
	v_mfma_f32_32x32x16_bf16 v[128:143], v[196:199], v[172:175], v[128:143]
	v_add3_u32 v196, s4, v225, v220
	ds_read_b128 v[192:195], v196
	ds_read_b128 v[196:199], v196 offset:8192
	s_waitcnt lgkmcnt(1)
	v_mfma_f32_32x32x16_bf16 v[144:159], v[192:195], v[176:179], v[144:159]
	s_waitcnt lgkmcnt(0)
	v_mfma_f32_32x32x16_bf16 v[128:143], v[196:199], v[176:179], v[128:143]
	v_add3_u32 v196, s4, v227, v220
	ds_read_b128 v[192:195], v196
	ds_read_b128 v[196:199], v196 offset:8192
	s_waitcnt lgkmcnt(1)
	v_mfma_f32_32x32x16_bf16 v[144:159], v[192:195], v[180:183], v[144:159]
	s_waitcnt lgkmcnt(0)
	v_mfma_f32_32x32x16_bf16 v[128:143], v[196:199], v[180:183], v[128:143]
	v_add3_u32 v196, s4, v228, v220
	ds_read_b128 v[192:195], v196
	ds_read_b128 v[196:199], v196 offset:8192
	s_waitcnt lgkmcnt(1)
	v_mfma_f32_32x32x16_bf16 v[144:159], v[192:195], v[184:187], v[144:159]
	s_waitcnt lgkmcnt(0)
	v_mfma_f32_32x32x16_bf16 v[128:143], v[196:199], v[184:187], v[128:143]
	v_add3_u32 v196, s4, v229, v220
	ds_read_b128 v[192:195], v196
	ds_read_b128 v[196:199], v196 offset:8192
	s_waitcnt lgkmcnt(1)
	v_mfma_f32_32x32x16_bf16 v[144:159], v[192:195], v[188:191], v[144:159]
	s_waitcnt lgkmcnt(0)
	v_mfma_f32_32x32x16_bf16 v[128:143], v[196:199], v[188:191], v[128:143]
	s_nop 9
	v_max_f32_e32 v192, v144, v145
	v_max3_f32 v192, v192, v146, v147
	v_max3_f32 v192, v192, v148, v149
	v_max3_f32 v192, v192, v150, v151
	v_max3_f32 v192, v192, v152, v153
	v_max3_f32 v192, v192, v154, v155
	v_max3_f32 v192, v192, v156, v157
	v_max3_f32 v192, v192, v158, v159
	v_max3_f32 v192, v192, v128, v129
	v_max3_f32 v192, v192, v130, v131
	v_max3_f32 v192, v192, v132, v133
	v_max3_f32 v192, v192, v134, v135
	v_max3_f32 v192, v192, v136, v137
	v_max3_f32 v192, v192, v138, v139
	v_max3_f32 v192, v192, v140, v141
	v_max3_f32 v192, v192, v142, v143
	v_mov_b32_e32 v193, v192
	s_nop 1
	v_permlane32_swap_b32_e32 v192, v193
	v_max_f32_e32 v192, v192, v193
	v_sub_f32_e32 v193, v192, v231
	v_cmp_ge_f32_e32 vcc, s38, v193
	v_max_f32_e32 v234, v231, v192
	v_sub_f32_e32 v192, v231, v234
	v_mul_f32_e32 v192, 0x3e0293ee, v192
	v_exp_f32_e32 v192, v192
	s_cmp_eq_u64 vcc, exec
	s_cselect_b64 s[4:5], -1, 0
	v_cndmask_b32_e64 v233, v192, 1.0, s[4:5]
	v_cmp_gt_f32_e32 vcc, 1.0, v233
	s_cbranch_vccz .LBB0_517
	s_and_saveexec_b64 s[24:25], s[0:1]
	ds_write_b32 v226, v233 offset:128
	s_or_b64 exec, exec, s[24:25]
	s_waitcnt lgkmcnt(0)
	v_add_u32_e32 v192, s21, v210
	ds_read_b128 v[204:207], v192 offset:224
	ds_read_b128 v[200:203], v192 offset:192
	ds_read_b128 v[196:199], v192 offset:160
	ds_read_b128 v[192:195], v192 offset:128
	s_waitcnt lgkmcnt(3)
	v_pk_mul_f32 v[12:13], v[12:13], v[204:205]
	s_waitcnt lgkmcnt(2)
	v_pk_mul_f32 v[8:9], v[8:9], v[200:201]
	s_waitcnt lgkmcnt(1)
	v_pk_mul_f32 v[4:5], v[4:5], v[196:197]
	v_pk_mul_f32 v[14:15], v[14:15], v[206:207]
	v_pk_mul_f32 v[10:11], v[10:11], v[202:203]
	v_pk_mul_f32 v[6:7], v[6:7], v[198:199]
	s_waitcnt lgkmcnt(0)
	v_pk_mul_f32 v[2:3], v[2:3], v[194:195]
	v_pk_mul_f32 v[0:1], v[0:1], v[192:193]
	v_pk_mul_f32 v[124:125], v[124:125], v[204:205]
	v_pk_mul_f32 v[120:121], v[120:121], v[200:201]
	v_pk_mul_f32 v[116:117], v[116:117], v[196:197]
	v_pk_mul_f32 v[126:127], v[126:127], v[206:207]
	v_pk_mul_f32 v[122:123], v[122:123], v[202:203]
	v_pk_mul_f32 v[118:119], v[118:119], v[198:199]
	v_pk_mul_f32 v[114:115], v[114:115], v[194:195]
	v_pk_mul_f32 v[112:113], v[112:113], v[192:193]
	v_pk_mul_f32 v[108:109], v[108:109], v[204:205]
	v_pk_mul_f32 v[104:105], v[104:105], v[200:201]
	v_pk_mul_f32 v[100:101], v[100:101], v[196:197]
	v_pk_mul_f32 v[110:111], v[110:111], v[206:207]
	v_pk_mul_f32 v[106:107], v[106:107], v[202:203]
	v_pk_mul_f32 v[102:103], v[102:103], v[198:199]
	v_pk_mul_f32 v[98:99], v[98:99], v[194:195]
	v_pk_mul_f32 v[96:97], v[96:97], v[192:193]
	v_pk_mul_f32 v[92:93], v[92:93], v[204:205]
	v_pk_mul_f32 v[88:89], v[88:89], v[200:201]
	v_pk_mul_f32 v[84:85], v[84:85], v[196:197]
	v_pk_mul_f32 v[94:95], v[94:95], v[206:207]
	v_pk_mul_f32 v[90:91], v[90:91], v[202:203]
	v_pk_mul_f32 v[86:87], v[86:87], v[198:199]
	v_pk_mul_f32 v[82:83], v[82:83], v[194:195]
	v_pk_mul_f32 v[80:81], v[80:81], v[192:193]
	v_pk_mul_f32 v[76:77], v[76:77], v[204:205]
	v_pk_mul_f32 v[72:73], v[72:73], v[200:201]
	v_pk_mul_f32 v[68:69], v[68:69], v[196:197]
	v_pk_mul_f32 v[78:79], v[78:79], v[206:207]
	v_pk_mul_f32 v[74:75], v[74:75], v[202:203]
	v_pk_mul_f32 v[70:71], v[70:71], v[198:199]
	v_pk_mul_f32 v[66:67], v[66:67], v[194:195]
	v_pk_mul_f32 v[64:65], v[64:65], v[192:193]
	v_pk_mul_f32 v[60:61], v[60:61], v[204:205]
	v_pk_mul_f32 v[56:57], v[56:57], v[200:201]
	v_pk_mul_f32 v[52:53], v[52:53], v[196:197]
	v_pk_mul_f32 v[62:63], v[62:63], v[206:207]
	v_pk_mul_f32 v[58:59], v[58:59], v[202:203]
	v_pk_mul_f32 v[54:55], v[54:55], v[198:199]
	v_pk_mul_f32 v[50:51], v[50:51], v[194:195]
	v_pk_mul_f32 v[48:49], v[48:49], v[192:193]
	v_pk_mul_f32 v[44:45], v[44:45], v[204:205]
	v_pk_mul_f32 v[40:41], v[40:41], v[200:201]
	v_pk_mul_f32 v[36:37], v[36:37], v[196:197]
	v_pk_mul_f32 v[46:47], v[46:47], v[206:207]
	v_pk_mul_f32 v[42:43], v[42:43], v[202:203]
	v_pk_mul_f32 v[38:39], v[38:39], v[198:199]
	v_pk_mul_f32 v[34:35], v[34:35], v[194:195]
	v_pk_mul_f32 v[32:33], v[32:33], v[192:193]
	v_pk_mul_f32 v[28:29], v[28:29], v[204:205]
	v_pk_mul_f32 v[24:25], v[24:25], v[200:201]
	v_pk_mul_f32 v[20:21], v[20:21], v[196:197]
	v_pk_mul_f32 v[30:31], v[30:31], v[206:207]
	v_pk_mul_f32 v[26:27], v[26:27], v[202:203]
	v_pk_mul_f32 v[22:23], v[22:23], v[198:199]
	v_pk_mul_f32 v[18:19], v[18:19], v[194:195]
	v_pk_mul_f32 v[16:17], v[16:17], v[192:193]
.LBB0_517:
	v_cndmask_b32_e64 v231, v234, v231, s[4:5]
	v_mul_f32_e32 v192, 0xbe0293ee, v231
	v_fmamk_f32 v144, v144, 0x3e0293ee, v192
	v_fmamk_f32 v145, v145, 0x3e0293ee, v192
	v_fmamk_f32 v146, v146, 0x3e0293ee, v192
	v_fmamk_f32 v147, v147, 0x3e0293ee, v192
	v_fmamk_f32 v148, v148, 0x3e0293ee, v192
	v_fmamk_f32 v149, v149, 0x3e0293ee, v192
	v_fmamk_f32 v150, v150, 0x3e0293ee, v192
	v_fmamk_f32 v151, v151, 0x3e0293ee, v192
	v_fmamk_f32 v152, v152, 0x3e0293ee, v192
	v_fmamk_f32 v153, v153, 0x3e0293ee, v192
	v_fmamk_f32 v154, v154, 0x3e0293ee, v192
	v_fmamk_f32 v155, v155, 0x3e0293ee, v192
	v_fmamk_f32 v156, v156, 0x3e0293ee, v192
	v_fmamk_f32 v157, v157, 0x3e0293ee, v192
	v_fmamk_f32 v158, v158, 0x3e0293ee, v192
	v_fmamk_f32 v159, v159, 0x3e0293ee, v192
	v_fmamk_f32 v128, v128, 0x3e0293ee, v192
	v_fmamk_f32 v129, v129, 0x3e0293ee, v192
	v_fmamk_f32 v130, v130, 0x3e0293ee, v192
	v_fmamk_f32 v131, v131, 0x3e0293ee, v192
	v_fmamk_f32 v132, v132, 0x3e0293ee, v192
	v_fmamk_f32 v133, v133, 0x3e0293ee, v192
	v_fmamk_f32 v134, v134, 0x3e0293ee, v192
	v_fmamk_f32 v135, v135, 0x3e0293ee, v192
	v_fmamk_f32 v136, v136, 0x3e0293ee, v192
	v_fmamk_f32 v137, v137, 0x3e0293ee, v192
	v_fmamk_f32 v138, v138, 0x3e0293ee, v192
	v_fmamk_f32 v139, v139, 0x3e0293ee, v192
	v_fmamk_f32 v140, v140, 0x3e0293ee, v192
	v_fmamk_f32 v141, v141, 0x3e0293ee, v192
	v_fmamk_f32 v142, v142, 0x3e0293ee, v192
	v_fmac_f32_e32 v192, 0x3e0293ee, v143
	v_exp_f32_e32 v143, v144
	v_exp_f32_e32 v145, v145
	v_exp_f32_e32 v146, v146
	v_exp_f32_e32 v147, v147
	v_exp_f32_e32 v148, v148
	v_exp_f32_e32 v193, v128
	v_exp_f32_e32 v149, v149
	v_add_f32_e32 v128, v145, v143
	v_exp_f32_e32 v150, v150
	v_add_f32_e32 v128, v146, v128
	v_exp_f32_e32 v151, v151
	v_add_f32_e32 v128, v147, v128
	v_exp_f32_e32 v152, v152
	v_add_f32_e32 v128, v148, v128
	v_exp_f32_e32 v153, v153
	v_add_f32_e32 v128, v149, v128
	v_exp_f32_e32 v154, v154
	v_add_f32_e32 v128, v150, v128
	v_exp_f32_e32 v155, v155
	v_add_f32_e32 v128, v151, v128
	v_exp_f32_e32 v156, v156
	v_add_f32_e32 v128, v152, v128
	v_exp_f32_e32 v157, v157
	v_add_f32_e32 v128, v153, v128
	v_exp_f32_e32 v158, v158
	v_add_f32_e32 v128, v154, v128
	v_exp_f32_e32 v159, v159
	v_add_f32_e32 v128, v155, v128
	v_add_f32_e32 v128, v156, v128
	v_exp_f32_e32 v194, v129
	v_add_f32_e32 v128, v157, v128
	v_exp_f32_e32 v195, v130
	v_add_f32_e32 v128, v158, v128
	v_exp_f32_e32 v196, v131
	v_add_f32_e32 v128, v159, v128
	v_exp_f32_e32 v197, v132
	v_add_f32_e32 v128, v193, v128
	v_exp_f32_e32 v198, v133
	v_add_f32_e32 v128, v194, v128
	v_exp_f32_e32 v199, v134
	v_add_f32_e32 v128, v195, v128
	v_exp_f32_e32 v135, v135
	v_add_f32_e32 v128, v196, v128
	v_exp_f32_e32 v200, v136
	v_add_f32_e32 v128, v197, v128
	v_exp_f32_e32 v201, v137
	v_add_f32_e32 v128, v198, v128
	v_exp_f32_e32 v202, v138
	v_add_f32_e32 v128, v199, v128
	v_exp_f32_e32 v203, v139
	v_add_f32_e32 v128, v135, v128
	v_exp_f32_e32 v204, v140
	v_add_f32_e32 v128, v200, v128
	v_exp_f32_e32 v205, v141
	v_add_f32_e32 v128, v201, v128
	v_exp_f32_e32 v206, v142
	v_add_f32_e32 v128, v202, v128
	v_exp_f32_e32 v192, v192
	v_add_f32_e32 v128, v203, v128
	v_add_f32_e32 v128, v204, v128
	v_add_f32_e32 v128, v205, v128
	v_add_f32_e32 v128, v206, v128
	v_add_f32_e32 v128, v192, v128
	v_mov_b32_e32 v129, v128
	s_nop 1
	v_permlane32_swap_b32_e32 v128, v129
	v_add_f32_e32 v144, v128, v129
	v_fmac_f32_e32 v144, v232, v233
	v_cvt_pk_bf16_f32 v128, v143, v145
	v_cvt_pk_bf16_f32 v129, v146, v147
	v_cvt_pk_bf16_f32 v130, v148, v149
	v_cvt_pk_bf16_f32 v131, v150, v151
	v_cvt_pk_bf16_f32 v136, v152, v153
	v_cvt_pk_bf16_f32 v137, v154, v155
	v_cvt_pk_bf16_f32 v138, v156, v157
	v_cvt_pk_bf16_f32 v139, v158, v159
	v_cvt_pk_bf16_f32 v132, v193, v194
	v_cvt_pk_bf16_f32 v133, v195, v196
	v_cvt_pk_bf16_f32 v134, v197, v198
	v_cvt_pk_bf16_f32 v135, v199, v135
	v_cvt_pk_bf16_f32 v140, v200, v201
	v_cvt_pk_bf16_f32 v141, v202, v203
	v_cvt_pk_bf16_f32 v142, v204, v205
	v_cvt_pk_bf16_f32 v143, v206, v192
	s_nop 0
	v_permlane32_swap_b32_e32 v128, v130
	v_permlane32_swap_b32_e32 v129, v131
	v_permlane32_swap_b32_e32 v136, v138
	v_permlane32_swap_b32_e32 v137, v139
	v_permlane32_swap_b32_e32 v132, v134
	v_permlane32_swap_b32_e32 v133, v135
	v_permlane32_swap_b32_e32 v140, v142
	v_permlane32_swap_b32_e32 v141, v143
	v_lshl_add_u32 v145, s76, 15, v230
	ds_read_b64_tr_b16 v[146:147], v145 offset:0
	ds_read_b64_tr_b16 v[148:149], v145 offset:0x1000
	ds_read_b64_tr_b16 v[150:151], v145 offset:0x2000
	ds_read_b64_tr_b16 v[152:153], v145 offset:0x3000
	ds_read_b64_tr_b16 v[154:155], v145 offset:0x4000
	ds_read_b64_tr_b16 v[156:157], v145 offset:0x5000
	ds_read_b64_tr_b16 v[192:193], v145 offset:0x6000
	ds_read_b64_tr_b16 v[194:195], v145 offset:0x7000
	ds_read_b64_tr_b16 v[196:197], v145 offset:0x200
	ds_read_b64_tr_b16 v[198:199], v145 offset:0x1200
	ds_read_b64_tr_b16 v[200:201], v145 offset:0x2200
	ds_read_b64_tr_b16 v[202:203], v145 offset:0x3200
	ds_read_b64_tr_b16 v[204:205], v145 offset:0x4200
	ds_read_b64_tr_b16 v[206:207], v145 offset:0x5200
	ds_read_b64_tr_b16 v[232:233], v145 offset:0x6200
	ds_read_b64_tr_b16 v[234:235], v145 offset:0x7200
	s_waitcnt lgkmcnt(8)
	s_nop 0
	v_mfma_f32_32x32x16_bf16 v[0:15], v[128:131], v[146:149], v[0:15]
	v_mfma_f32_32x32x16_bf16 v[0:15], v[136:139], v[150:153], v[0:15]
	v_mfma_f32_32x32x16_bf16 v[0:15], v[132:135], v[154:157], v[0:15]
	v_mfma_f32_32x32x16_bf16 v[0:15], v[140:143], v[192:195], v[0:15]
	ds_read_b64_tr_b16 v[146:147], v145 offset:0x400
	ds_read_b64_tr_b16 v[148:149], v145 offset:0x1400
	ds_read_b64_tr_b16 v[150:151], v145 offset:0x2400
	ds_read_b64_tr_b16 v[152:153], v145 offset:0x3400
	ds_read_b64_tr_b16 v[154:155], v145 offset:0x4400
	ds_read_b64_tr_b16 v[156:157], v145 offset:0x5400
	ds_read_b64_tr_b16 v[192:193], v145 offset:0x6400
	ds_read_b64_tr_b16 v[194:195], v145 offset:0x7400
	s_waitcnt lgkmcnt(8)
	v_mfma_f32_32x32x16_bf16 v[112:127], v[128:131], v[196:199], v[112:127]
	v_mfma_f32_32x32x16_bf16 v[112:127], v[136:139], v[200:203], v[112:127]
	v_mfma_f32_32x32x16_bf16 v[112:127], v[132:135], v[204:207], v[112:127]
	v_mfma_f32_32x32x16_bf16 v[112:127], v[140:143], v[232:235], v[112:127]
	ds_read_b64_tr_b16 v[196:197], v145 offset:0x600
	ds_read_b64_tr_b16 v[198:199], v145 offset:0x1600
	ds_read_b64_tr_b16 v[200:201], v145 offset:0x2600
	ds_read_b64_tr_b16 v[202:203], v145 offset:0x3600
	ds_read_b64_tr_b16 v[204:205], v145 offset:0x4600
	ds_read_b64_tr_b16 v[206:207], v145 offset:0x5600
	ds_read_b64_tr_b16 v[232:233], v145 offset:0x6600
	ds_read_b64_tr_b16 v[234:235], v145 offset:0x7600
	s_waitcnt lgkmcnt(8)
	v_mfma_f32_32x32x16_bf16 v[96:111], v[128:131], v[146:149], v[96:111]
	v_mfma_f32_32x32x16_bf16 v[96:111], v[136:139], v[150:153], v[96:111]
	v_mfma_f32_32x32x16_bf16 v[96:111], v[132:135], v[154:157], v[96:111]
	v_mfma_f32_32x32x16_bf16 v[96:111], v[140:143], v[192:195], v[96:111]
	ds_read_b64_tr_b16 v[146:147], v145 offset:0x800
	ds_read_b64_tr_b16 v[148:149], v145 offset:0x1800
	ds_read_b64_tr_b16 v[150:151], v145 offset:0x2800
	ds_read_b64_tr_b16 v[152:153], v145 offset:0x3800
	ds_read_b64_tr_b16 v[154:155], v145 offset:0x4800
	ds_read_b64_tr_b16 v[156:157], v145 offset:0x5800
	ds_read_b64_tr_b16 v[192:193], v145 offset:0x6800
	ds_read_b64_tr_b16 v[194:195], v145 offset:0x7800
	s_waitcnt lgkmcnt(8)
	v_mfma_f32_32x32x16_bf16 v[80:95], v[128:131], v[196:199], v[80:95]
	v_mfma_f32_32x32x16_bf16 v[80:95], v[136:139], v[200:203], v[80:95]
	v_mfma_f32_32x32x16_bf16 v[80:95], v[132:135], v[204:207], v[80:95]
	v_mfma_f32_32x32x16_bf16 v[80:95], v[140:143], v[232:235], v[80:95]
	ds_read_b64_tr_b16 v[196:197], v145 offset:0xa00
	ds_read_b64_tr_b16 v[198:199], v145 offset:0x1a00
	ds_read_b64_tr_b16 v[200:201], v145 offset:0x2a00
	ds_read_b64_tr_b16 v[202:203], v145 offset:0x3a00
	ds_read_b64_tr_b16 v[204:205], v145 offset:0x4a00
	ds_read_b64_tr_b16 v[206:207], v145 offset:0x5a00
	ds_read_b64_tr_b16 v[232:233], v145 offset:0x6a00
	ds_read_b64_tr_b16 v[234:235], v145 offset:0x7a00
	s_waitcnt lgkmcnt(8)
	v_mfma_f32_32x32x16_bf16 v[64:79], v[128:131], v[146:149], v[64:79]
	v_mfma_f32_32x32x16_bf16 v[64:79], v[136:139], v[150:153], v[64:79]
	v_mfma_f32_32x32x16_bf16 v[64:79], v[132:135], v[154:157], v[64:79]
	v_mfma_f32_32x32x16_bf16 v[64:79], v[140:143], v[192:195], v[64:79]
	ds_read_b64_tr_b16 v[146:147], v145 offset:0xc00
	ds_read_b64_tr_b16 v[148:149], v145 offset:0x1c00
	ds_read_b64_tr_b16 v[150:151], v145 offset:0x2c00
	ds_read_b64_tr_b16 v[152:153], v145 offset:0x3c00
	ds_read_b64_tr_b16 v[154:155], v145 offset:0x4c00
	ds_read_b64_tr_b16 v[156:157], v145 offset:0x5c00
	ds_read_b64_tr_b16 v[192:193], v145 offset:0x6c00
	ds_read_b64_tr_b16 v[194:195], v145 offset:0x7c00
	s_waitcnt lgkmcnt(8)
	v_mfma_f32_32x32x16_bf16 v[48:63], v[128:131], v[196:199], v[48:63]
	v_mfma_f32_32x32x16_bf16 v[48:63], v[136:139], v[200:203], v[48:63]
	v_mfma_f32_32x32x16_bf16 v[48:63], v[132:135], v[204:207], v[48:63]
	v_mfma_f32_32x32x16_bf16 v[48:63], v[140:143], v[232:235], v[48:63]
	ds_read_b64_tr_b16 v[196:197], v145 offset:0xe00
	ds_read_b64_tr_b16 v[198:199], v145 offset:0x1e00
	ds_read_b64_tr_b16 v[200:201], v145 offset:0x2e00
	ds_read_b64_tr_b16 v[202:203], v145 offset:0x3e00
	ds_read_b64_tr_b16 v[204:205], v145 offset:0x4e00
	ds_read_b64_tr_b16 v[206:207], v145 offset:0x5e00
	ds_read_b64_tr_b16 v[232:233], v145 offset:0x6e00
	ds_read_b64_tr_b16 v[234:235], v145 offset:0x7e00
	s_waitcnt lgkmcnt(8)
	v_mfma_f32_32x32x16_bf16 v[32:47], v[128:131], v[146:149], v[32:47]
	v_mfma_f32_32x32x16_bf16 v[32:47], v[136:139], v[150:153], v[32:47]
	v_mfma_f32_32x32x16_bf16 v[32:47], v[132:135], v[154:157], v[32:47]
	v_mfma_f32_32x32x16_bf16 v[32:47], v[140:143], v[192:195], v[32:47]
	s_waitcnt lgkmcnt(0)
	v_mfma_f32_32x32x16_bf16 v[16:31], v[128:131], v[196:199], v[16:31]
	s_add_i32 s4, s76, 1
	s_cmp_lg_u32 s76, 2
	s_cselect_b32 s76, s4, 0
	s_add_i32 s4, s74, 1
	s_cmp_lg_u32 s74, 2
	s_cselect_b32 s74, s4, 0
	s_add_u32 s22, s22, 0x20000
	v_mfma_f32_32x32x16_bf16 v[16:31], v[136:139], v[200:203], v[16:31]
	s_addc_u32 s23, s23, 0
	s_add_i32 s86, s86, 1
	s_cmp_eq_u32 s22, 0x800000
	v_mfma_f32_32x32x16_bf16 v[16:31], v[132:135], v[204:207], v[16:31]
	v_mfma_f32_32x32x16_bf16 v[16:31], v[140:143], v[232:235], v[16:31]
	s_cbranch_scc1 .LBB0_521
	v_mov_b32_e32 v232, v144
	s_cmp_eq_u32 s22, 0x7e0000
	s_mov_b64 s[4:5], -1
	s_cbranch_scc1 .LBB0_510

.LBB0_906:
	s_lshl_b32 s4, s80, 14
	s_add_i32 s4, s4, 0
	v_add3_u32 v132, s4, v221, v220
	ds_read_b128 v[128:131], v132
	ds_read_b128 v[132:135], v132 offset:8192
	v_add3_u32 v196, s4, v222, v220
	ds_read_b128 v[192:195], v196
	ds_read_b128 v[196:199], v196 offset:8192
	v_add3_u32 v200, s4, v227, v220
	s_waitcnt lgkmcnt(3)
	v_mfma_f32_32x32x16_bf16 v[144:159], v[128:131], v[160:163], 0
	s_waitcnt lgkmcnt(2)
	v_mfma_f32_32x32x16_bf16 v[128:143], v[132:135], v[160:163], 0
	s_waitcnt lgkmcnt(1)
	v_mfma_f32_32x32x16_bf16 v[144:159], v[192:195], v[164:167], v[144:159]
	s_waitcnt lgkmcnt(0)
	v_mfma_f32_32x32x16_bf16 v[128:143], v[196:199], v[164:167], v[128:143]
	v_add3_u32 v196, s4, v223, v220
	ds_read_b128 v[192:195], v196
	ds_read_b128 v[196:199], v196 offset:8192
	s_waitcnt lgkmcnt(1)
	v_mfma_f32_32x32x16_bf16 v[144:159], v[192:195], v[168:171], v[144:159]
	s_waitcnt lgkmcnt(0)
	v_mfma_f32_32x32x16_bf16 v[128:143], v[196:199], v[168:171], v[128:143]
	v_add3_u32 v196, s4, v225, v220
	ds_read_b128 v[192:195], v196
	ds_read_b128 v[196:199], v196 offset:8192
	s_waitcnt lgkmcnt(1)
	v_mfma_f32_32x32x16_bf16 v[144:159], v[192:195], v[172:175], v[144:159]
	s_waitcnt lgkmcnt(0)
	v_mfma_f32_32x32x16_bf16 v[128:143], v[196:199], v[172:175], v[128:143]
	v_add3_u32 v196, s4, v226, v220
	ds_read_b128 v[192:195], v196
	ds_read_b128 v[196:199], v196 offset:8192
	s_waitcnt lgkmcnt(1)
	v_mfma_f32_32x32x16_bf16 v[144:159], v[192:195], v[176:179], v[144:159]
	s_waitcnt lgkmcnt(0)
	v_mfma_f32_32x32x16_bf16 v[128:143], v[196:199], v[176:179], v[128:143]
	ds_read_b128 v[192:195], v200
	ds_read_b128 v[196:199], v200 offset:8192
	v_add3_u32 v200, s4, v228, v220
	s_waitcnt lgkmcnt(1)
	v_mfma_f32_32x32x16_bf16 v[144:159], v[192:195], v[180:183], v[144:159]
	s_waitcnt lgkmcnt(0)
	v_mfma_f32_32x32x16_bf16 v[128:143], v[196:199], v[180:183], v[128:143]
	ds_read_b128 v[192:195], v200
	ds_read_b128 v[196:199], v200 offset:8192
	v_add3_u32 v200, s4, v229, v220
	s_waitcnt lgkmcnt(1)
	v_mfma_f32_32x32x16_bf16 v[144:159], v[192:195], v[184:187], v[144:159]
	ds_read_b128 v[192:195], v200
	ds_read_b128 v[200:203], v200 offset:8192
	s_waitcnt lgkmcnt(1)
	v_mfma_f32_32x32x16_bf16 v[144:159], v[192:195], v[188:191], v[144:159]
	v_max_f32_e32 v194, v231, v231
	v_mfma_f32_32x32x16_bf16 v[128:143], v[196:199], v[184:187], v[128:143]
	s_nop 9
	v_max_f32_e32 v192, v144, v145
	v_max3_f32 v192, v192, v146, v147
	v_max3_f32 v192, v192, v148, v149
	v_max3_f32 v192, v192, v150, v151
	v_max3_f32 v192, v192, v152, v153
	s_waitcnt lgkmcnt(0)
	v_mfma_f32_32x32x16_bf16 v[128:143], v[200:203], v[188:191], v[128:143]
	v_max3_f32 v192, v192, v154, v155
	v_max3_f32 v192, v192, v156, v157
	v_max3_f32 v192, v192, v158, v159
	s_nop 8
	v_max3_f32 v192, v192, v128, v129
	v_max3_f32 v192, v192, v130, v131
	v_max3_f32 v192, v192, v132, v133
	v_max3_f32 v192, v192, v134, v135
	v_max3_f32 v192, v192, v136, v137
	v_max3_f32 v192, v192, v138, v139
	v_max3_f32 v192, v192, v140, v141
	v_max3_f32 v192, v192, v142, v143
	v_mov_b32_e32 v193, v192
	s_nop 1
	v_permlane32_swap_b32_e32 v192, v193
	v_max_f32_e32 v192, v192, v193
	v_max_f32_e32 v234, v194, v192
	v_sub_f32_e32 v193, v192, v231
	v_sub_f32_e32 v192, v231, v234
	v_mul_f32_e32 v192, 0x3e0293ee, v192
	v_exp_f32_e32 v192, v192
	v_cmp_ge_f32_e32 vcc, s42, v193
	s_cmp_eq_u64 vcc, exec
	s_cselect_b64 s[4:5], -1, 0
	v_cndmask_b32_e64 v233, v192, 1.0, s[4:5]
	v_cmp_gt_f32_e32 vcc, 1.0, v233
	s_cbranch_vccz .LBB0_910
	s_and_saveexec_b64 s[24:25], s[0:1]
	ds_write_b32 v224, v233 offset:128
	s_or_b64 exec, exec, s[24:25]
	s_waitcnt lgkmcnt(0)
	v_add_u32_e32 v192, s21, v210
	ds_read_b128 v[204:207], v192 offset:224
	ds_read_b128 v[200:203], v192 offset:192
	ds_read_b128 v[196:199], v192 offset:160
	ds_read_b128 v[192:195], v192 offset:128
	s_waitcnt lgkmcnt(3)
	v_pk_mul_f32 v[12:13], v[12:13], v[204:205]
	s_waitcnt lgkmcnt(2)
	v_pk_mul_f32 v[8:9], v[8:9], v[200:201]
	s_waitcnt lgkmcnt(1)
	v_pk_mul_f32 v[4:5], v[4:5], v[196:197]
	v_pk_mul_f32 v[14:15], v[14:15], v[206:207]
	v_pk_mul_f32 v[10:11], v[10:11], v[202:203]
	v_pk_mul_f32 v[6:7], v[6:7], v[198:199]
	s_waitcnt lgkmcnt(0)
	v_pk_mul_f32 v[2:3], v[2:3], v[194:195]
	v_pk_mul_f32 v[0:1], v[0:1], v[192:193]
	v_pk_mul_f32 v[124:125], v[124:125], v[204:205]
	v_pk_mul_f32 v[120:121], v[120:121], v[200:201]
	v_pk_mul_f32 v[116:117], v[116:117], v[196:197]
	v_pk_mul_f32 v[126:127], v[126:127], v[206:207]
	v_pk_mul_f32 v[122:123], v[122:123], v[202:203]
	v_pk_mul_f32 v[118:119], v[118:119], v[198:199]
	v_pk_mul_f32 v[114:115], v[114:115], v[194:195]
	v_pk_mul_f32 v[112:113], v[112:113], v[192:193]
	v_pk_mul_f32 v[108:109], v[108:109], v[204:205]
	v_pk_mul_f32 v[104:105], v[104:105], v[200:201]
	v_pk_mul_f32 v[100:101], v[100:101], v[196:197]
	v_pk_mul_f32 v[110:111], v[110:111], v[206:207]
	v_pk_mul_f32 v[106:107], v[106:107], v[202:203]
	v_pk_mul_f32 v[102:103], v[102:103], v[198:199]
	v_pk_mul_f32 v[98:99], v[98:99], v[194:195]
	v_pk_mul_f32 v[96:97], v[96:97], v[192:193]
	v_pk_mul_f32 v[92:93], v[92:93], v[204:205]
	v_pk_mul_f32 v[88:89], v[88:89], v[200:201]
	v_pk_mul_f32 v[84:85], v[84:85], v[196:197]
	v_pk_mul_f32 v[94:95], v[94:95], v[206:207]
	v_pk_mul_f32 v[90:91], v[90:91], v[202:203]
	v_pk_mul_f32 v[86:87], v[86:87], v[198:199]
	v_pk_mul_f32 v[82:83], v[82:83], v[194:195]
	v_pk_mul_f32 v[80:81], v[80:81], v[192:193]
	v_pk_mul_f32 v[76:77], v[76:77], v[204:205]
	v_pk_mul_f32 v[72:73], v[72:73], v[200:201]
	v_pk_mul_f32 v[68:69], v[68:69], v[196:197]
	v_pk_mul_f32 v[78:79], v[78:79], v[206:207]
	v_pk_mul_f32 v[74:75], v[74:75], v[202:203]
	v_pk_mul_f32 v[70:71], v[70:71], v[198:199]
	v_pk_mul_f32 v[66:67], v[66:67], v[194:195]
	v_pk_mul_f32 v[64:65], v[64:65], v[192:193]
	v_pk_mul_f32 v[60:61], v[60:61], v[204:205]
	v_pk_mul_f32 v[56:57], v[56:57], v[200:201]
	v_pk_mul_f32 v[52:53], v[52:53], v[196:197]
	v_pk_mul_f32 v[62:63], v[62:63], v[206:207]
	v_pk_mul_f32 v[58:59], v[58:59], v[202:203]
	v_pk_mul_f32 v[54:55], v[54:55], v[198:199]
	v_pk_mul_f32 v[50:51], v[50:51], v[194:195]
	v_pk_mul_f32 v[48:49], v[48:49], v[192:193]
	v_pk_mul_f32 v[44:45], v[44:45], v[204:205]
	v_pk_mul_f32 v[40:41], v[40:41], v[200:201]
	v_pk_mul_f32 v[36:37], v[36:37], v[196:197]
	v_pk_mul_f32 v[46:47], v[46:47], v[206:207]
	v_pk_mul_f32 v[42:43], v[42:43], v[202:203]
	v_pk_mul_f32 v[38:39], v[38:39], v[198:199]
	v_pk_mul_f32 v[34:35], v[34:35], v[194:195]
	v_pk_mul_f32 v[32:33], v[32:33], v[192:193]
	v_pk_mul_f32 v[28:29], v[28:29], v[204:205]
	v_pk_mul_f32 v[24:25], v[24:25], v[200:201]
	v_pk_mul_f32 v[20:21], v[20:21], v[196:197]
	v_pk_mul_f32 v[30:31], v[30:31], v[206:207]
	v_pk_mul_f32 v[26:27], v[26:27], v[202:203]
	v_pk_mul_f32 v[22:23], v[22:23], v[198:199]
	v_pk_mul_f32 v[18:19], v[18:19], v[194:195]
	v_pk_mul_f32 v[16:17], v[16:17], v[192:193]
.LBB0_910:
	v_cndmask_b32_e64 v231, v234, v231, s[4:5]
	v_mul_f32_e32 v192, 0xbe0293ee, v231
	v_fmamk_f32 v144, v144, 0x3e0293ee, v192
	v_fmamk_f32 v145, v145, 0x3e0293ee, v192
	v_fmamk_f32 v146, v146, 0x3e0293ee, v192
	v_fmamk_f32 v147, v147, 0x3e0293ee, v192
	v_fmamk_f32 v148, v148, 0x3e0293ee, v192
	v_fmamk_f32 v149, v149, 0x3e0293ee, v192
	v_fmamk_f32 v150, v150, 0x3e0293ee, v192
	v_fmamk_f32 v151, v151, 0x3e0293ee, v192
	v_fmamk_f32 v152, v152, 0x3e0293ee, v192
	v_fmamk_f32 v153, v153, 0x3e0293ee, v192
	v_fmamk_f32 v154, v154, 0x3e0293ee, v192
	v_fmamk_f32 v155, v155, 0x3e0293ee, v192
	v_fmamk_f32 v156, v156, 0x3e0293ee, v192
	v_fmamk_f32 v157, v157, 0x3e0293ee, v192
	v_fmamk_f32 v158, v158, 0x3e0293ee, v192
	v_fmamk_f32 v159, v159, 0x3e0293ee, v192
	v_fmamk_f32 v128, v128, 0x3e0293ee, v192
	v_fmamk_f32 v129, v129, 0x3e0293ee, v192
	v_fmamk_f32 v130, v130, 0x3e0293ee, v192
	v_fmamk_f32 v131, v131, 0x3e0293ee, v192
	v_fmamk_f32 v132, v132, 0x3e0293ee, v192
	v_fmamk_f32 v133, v133, 0x3e0293ee, v192
	v_fmamk_f32 v134, v134, 0x3e0293ee, v192
	v_fmamk_f32 v135, v135, 0x3e0293ee, v192
	v_fmamk_f32 v136, v136, 0x3e0293ee, v192
	v_fmamk_f32 v137, v137, 0x3e0293ee, v192
	v_fmamk_f32 v138, v138, 0x3e0293ee, v192
	v_fmamk_f32 v139, v139, 0x3e0293ee, v192
	v_fmamk_f32 v140, v140, 0x3e0293ee, v192
	v_fmamk_f32 v141, v141, 0x3e0293ee, v192
	v_fmamk_f32 v142, v142, 0x3e0293ee, v192
	v_fmac_f32_e32 v192, 0x3e0293ee, v143
	v_exp_f32_e32 v143, v144
	v_exp_f32_e32 v145, v145
	v_exp_f32_e32 v146, v146
	v_exp_f32_e32 v147, v147
	v_exp_f32_e32 v148, v148
	v_exp_f32_e32 v193, v128
	v_exp_f32_e32 v149, v149
	v_add_f32_e32 v128, v145, v143
	v_exp_f32_e32 v150, v150
	v_add_f32_e32 v128, v146, v128
	v_exp_f32_e32 v151, v151
	v_add_f32_e32 v128, v147, v128
	v_exp_f32_e32 v152, v152
	v_add_f32_e32 v128, v148, v128
	v_exp_f32_e32 v153, v153
	v_add_f32_e32 v128, v149, v128
	v_exp_f32_e32 v154, v154
	v_add_f32_e32 v128, v150, v128
	v_exp_f32_e32 v155, v155
	v_add_f32_e32 v128, v151, v128
	v_exp_f32_e32 v156, v156
	v_add_f32_e32 v128, v152, v128
	v_exp_f32_e32 v157, v157
	v_add_f32_e32 v128, v153, v128
	v_exp_f32_e32 v158, v158
	v_add_f32_e32 v128, v154, v128
	v_exp_f32_e32 v159, v159
	v_add_f32_e32 v128, v155, v128
	v_add_f32_e32 v128, v156, v128
	v_exp_f32_e32 v194, v129
	v_add_f32_e32 v128, v157, v128
	v_exp_f32_e32 v195, v130
	v_add_f32_e32 v128, v158, v128
	v_exp_f32_e32 v196, v131
	v_add_f32_e32 v128, v159, v128
	v_exp_f32_e32 v197, v132
	v_add_f32_e32 v128, v193, v128
	v_exp_f32_e32 v198, v133
	v_add_f32_e32 v128, v194, v128
	v_exp_f32_e32 v199, v134
	v_add_f32_e32 v128, v195, v128
	v_exp_f32_e32 v135, v135
	v_add_f32_e32 v128, v196, v128
	v_exp_f32_e32 v200, v136
	v_add_f32_e32 v128, v197, v128
	v_exp_f32_e32 v201, v137
	v_add_f32_e32 v128, v198, v128
	v_exp_f32_e32 v202, v138
	v_add_f32_e32 v128, v199, v128
	v_exp_f32_e32 v203, v139
	v_add_f32_e32 v128, v135, v128
	v_exp_f32_e32 v204, v140
	v_add_f32_e32 v128, v200, v128
	v_exp_f32_e32 v205, v141
	v_add_f32_e32 v128, v201, v128
	v_exp_f32_e32 v206, v142
	v_add_f32_e32 v128, v202, v128
	v_exp_f32_e32 v192, v192
	v_add_f32_e32 v128, v203, v128
	v_add_f32_e32 v128, v204, v128
	v_add_f32_e32 v128, v205, v128
	v_add_f32_e32 v128, v206, v128
	v_add_f32_e32 v128, v192, v128
	v_mov_b32_e32 v129, v128
	s_nop 1
	v_permlane32_swap_b32_e32 v128, v129
	v_add_f32_e32 v144, v128, v129
	v_fmac_f32_e32 v144, v232, v233
	v_cvt_pk_bf16_f32 v128, v143, v145
	v_cvt_pk_bf16_f32 v129, v146, v147
	v_cvt_pk_bf16_f32 v130, v148, v149
	v_cvt_pk_bf16_f32 v131, v150, v151
	v_cvt_pk_bf16_f32 v136, v152, v153
	v_cvt_pk_bf16_f32 v137, v154, v155
	v_cvt_pk_bf16_f32 v138, v156, v157
	v_cvt_pk_bf16_f32 v139, v158, v159
	v_cvt_pk_bf16_f32 v132, v193, v194
	v_cvt_pk_bf16_f32 v133, v195, v196
	v_cvt_pk_bf16_f32 v134, v197, v198
	v_cvt_pk_bf16_f32 v135, v199, v135
	v_cvt_pk_bf16_f32 v140, v200, v201
	v_cvt_pk_bf16_f32 v141, v202, v203
	v_cvt_pk_bf16_f32 v142, v204, v205
	v_cvt_pk_bf16_f32 v143, v206, v192
	s_nop 0
	v_permlane32_swap_b32_e32 v128, v130
	v_permlane32_swap_b32_e32 v129, v131
	v_permlane32_swap_b32_e32 v136, v138
	v_permlane32_swap_b32_e32 v137, v139
	v_permlane32_swap_b32_e32 v132, v134
	v_permlane32_swap_b32_e32 v133, v135
	v_permlane32_swap_b32_e32 v140, v142
	v_permlane32_swap_b32_e32 v141, v143
	v_lshl_add_u32 v145, s80, 15, v230
	ds_read_b64_tr_b16 v[146:147], v145 offset:0
	ds_read_b64_tr_b16 v[148:149], v145 offset:0x1000
	ds_read_b64_tr_b16 v[150:151], v145 offset:0x2000
	ds_read_b64_tr_b16 v[152:153], v145 offset:0x3000
	ds_read_b64_tr_b16 v[154:155], v145 offset:0x4000
	ds_read_b64_tr_b16 v[156:157], v145 offset:0x5000
	ds_read_b64_tr_b16 v[192:193], v145 offset:0x6000
	ds_read_b64_tr_b16 v[194:195], v145 offset:0x7000
	ds_read_b64_tr_b16 v[196:197], v145 offset:0x200
	ds_read_b64_tr_b16 v[198:199], v145 offset:0x1200
	ds_read_b64_tr_b16 v[200:201], v145 offset:0x2200
	ds_read_b64_tr_b16 v[202:203], v145 offset:0x3200
	ds_read_b64_tr_b16 v[204:205], v145 offset:0x4200
	ds_read_b64_tr_b16 v[206:207], v145 offset:0x5200
	ds_read_b64_tr_b16 v[232:233], v145 offset:0x6200
	ds_read_b64_tr_b16 v[234:235], v145 offset:0x7200
	s_waitcnt lgkmcnt(8)
	s_nop 0
	v_mfma_f32_32x32x16_bf16 v[0:15], v[128:131], v[146:149], v[0:15]
	v_mfma_f32_32x32x16_bf16 v[0:15], v[136:139], v[150:153], v[0:15]
	v_mfma_f32_32x32x16_bf16 v[0:15], v[132:135], v[154:157], v[0:15]
	v_mfma_f32_32x32x16_bf16 v[0:15], v[140:143], v[192:195], v[0:15]
	ds_read_b64_tr_b16 v[146:147], v145 offset:0x400
	ds_read_b64_tr_b16 v[148:149], v145 offset:0x1400
	ds_read_b64_tr_b16 v[150:151], v145 offset:0x2400
	ds_read_b64_tr_b16 v[152:153], v145 offset:0x3400
	ds_read_b64_tr_b16 v[154:155], v145 offset:0x4400
	ds_read_b64_tr_b16 v[156:157], v145 offset:0x5400
	ds_read_b64_tr_b16 v[192:193], v145 offset:0x6400
	ds_read_b64_tr_b16 v[194:195], v145 offset:0x7400
	s_waitcnt lgkmcnt(8)
	v_mfma_f32_32x32x16_bf16 v[112:127], v[128:131], v[196:199], v[112:127]
	v_mfma_f32_32x32x16_bf16 v[112:127], v[136:139], v[200:203], v[112:127]
	v_mfma_f32_32x32x16_bf16 v[112:127], v[132:135], v[204:207], v[112:127]
	v_mfma_f32_32x32x16_bf16 v[112:127], v[140:143], v[232:235], v[112:127]
	ds_read_b64_tr_b16 v[196:197], v145 offset:0x600
	ds_read_b64_tr_b16 v[198:199], v145 offset:0x1600
	ds_read_b64_tr_b16 v[200:201], v145 offset:0x2600
	ds_read_b64_tr_b16 v[202:203], v145 offset:0x3600
	ds_read_b64_tr_b16 v[204:205], v145 offset:0x4600
	ds_read_b64_tr_b16 v[206:207], v145 offset:0x5600
	ds_read_b64_tr_b16 v[232:233], v145 offset:0x6600
	ds_read_b64_tr_b16 v[234:235], v145 offset:0x7600
	s_waitcnt lgkmcnt(8)
	v_mfma_f32_32x32x16_bf16 v[96:111], v[128:131], v[146:149], v[96:111]
	v_mfma_f32_32x32x16_bf16 v[96:111], v[136:139], v[150:153], v[96:111]
	v_mfma_f32_32x32x16_bf16 v[96:111], v[132:135], v[154:157], v[96:111]
	v_mfma_f32_32x32x16_bf16 v[96:111], v[140:143], v[192:195], v[96:111]
	ds_read_b64_tr_b16 v[146:147], v145 offset:0x800
	ds_read_b64_tr_b16 v[148:149], v145 offset:0x1800
	ds_read_b64_tr_b16 v[150:151], v145 offset:0x2800
	ds_read_b64_tr_b16 v[152:153], v145 offset:0x3800
	ds_read_b64_tr_b16 v[154:155], v145 offset:0x4800
	ds_read_b64_tr_b16 v[156:157], v145 offset:0x5800
	ds_read_b64_tr_b16 v[192:193], v145 offset:0x6800
	ds_read_b64_tr_b16 v[194:195], v145 offset:0x7800
	s_waitcnt lgkmcnt(8)
	v_mfma_f32_32x32x16_bf16 v[80:95], v[128:131], v[196:199], v[80:95]
	v_mfma_f32_32x32x16_bf16 v[80:95], v[136:139], v[200:203], v[80:95]
	v_mfma_f32_32x32x16_bf16 v[80:95], v[132:135], v[204:207], v[80:95]
	v_mfma_f32_32x32x16_bf16 v[80:95], v[140:143], v[232:235], v[80:95]
	ds_read_b64_tr_b16 v[196:197], v145 offset:0xa00
	ds_read_b64_tr_b16 v[198:199], v145 offset:0x1a00
	ds_read_b64_tr_b16 v[200:201], v145 offset:0x2a00
	ds_read_b64_tr_b16 v[202:203], v145 offset:0x3a00
	ds_read_b64_tr_b16 v[204:205], v145 offset:0x4a00
	ds_read_b64_tr_b16 v[206:207], v145 offset:0x5a00
	ds_read_b64_tr_b16 v[232:233], v145 offset:0x6a00
	ds_read_b64_tr_b16 v[234:235], v145 offset:0x7a00
	s_waitcnt lgkmcnt(8)
	v_mfma_f32_32x32x16_bf16 v[64:79], v[128:131], v[146:149], v[64:79]
	v_mfma_f32_32x32x16_bf16 v[64:79], v[136:139], v[150:153], v[64:79]
	v_mfma_f32_32x32x16_bf16 v[64:79], v[132:135], v[154:157], v[64:79]
	v_mfma_f32_32x32x16_bf16 v[64:79], v[140:143], v[192:195], v[64:79]
	ds_read_b64_tr_b16 v[146:147], v145 offset:0xc00
	ds_read_b64_tr_b16 v[148:149], v145 offset:0x1c00
	ds_read_b64_tr_b16 v[150:151], v145 offset:0x2c00
	ds_read_b64_tr_b16 v[152:153], v145 offset:0x3c00
	ds_read_b64_tr_b16 v[154:155], v145 offset:0x4c00
	ds_read_b64_tr_b16 v[156:157], v145 offset:0x5c00
	ds_read_b64_tr_b16 v[192:193], v145 offset:0x6c00
	ds_read_b64_tr_b16 v[194:195], v145 offset:0x7c00
	s_waitcnt lgkmcnt(8)
	v_mfma_f32_32x32x16_bf16 v[48:63], v[128:131], v[196:199], v[48:63]
	v_mfma_f32_32x32x16_bf16 v[48:63], v[136:139], v[200:203], v[48:63]
	v_mfma_f32_32x32x16_bf16 v[48:63], v[132:135], v[204:207], v[48:63]
	v_mfma_f32_32x32x16_bf16 v[48:63], v[140:143], v[232:235], v[48:63]
	ds_read_b64_tr_b16 v[196:197], v145 offset:0xe00
	ds_read_b64_tr_b16 v[198:199], v145 offset:0x1e00
	ds_read_b64_tr_b16 v[200:201], v145 offset:0x2e00
	ds_read_b64_tr_b16 v[202:203], v145 offset:0x3e00
	ds_read_b64_tr_b16 v[204:205], v145 offset:0x4e00
	ds_read_b64_tr_b16 v[206:207], v145 offset:0x5e00
	ds_read_b64_tr_b16 v[232:233], v145 offset:0x6e00
	ds_read_b64_tr_b16 v[234:235], v145 offset:0x7e00
	s_waitcnt lgkmcnt(8)
	v_mfma_f32_32x32x16_bf16 v[32:47], v[128:131], v[146:149], v[32:47]
	v_mfma_f32_32x32x16_bf16 v[32:47], v[136:139], v[150:153], v[32:47]
	v_mfma_f32_32x32x16_bf16 v[32:47], v[132:135], v[154:157], v[32:47]
	v_mfma_f32_32x32x16_bf16 v[32:47], v[140:143], v[192:195], v[32:47]
	s_waitcnt lgkmcnt(0)
	v_mfma_f32_32x32x16_bf16 v[16:31], v[128:131], v[196:199], v[16:31]
	s_add_i32 s4, s80, 1
	s_cmp_lg_u32 s80, 2
	s_cselect_b32 s80, s4, 0
	s_add_i32 s4, s78, 1
	s_cmp_lg_u32 s78, 2
	s_cselect_b32 s78, s4, 0
	s_add_u32 s22, s22, 0x20000
	v_mfma_f32_32x32x16_bf16 v[16:31], v[136:139], v[200:203], v[16:31]
	s_addc_u32 s23, s23, 0
	s_add_i32 s86, s86, 1
	s_cmp_eq_u32 s22, 0x800000
	v_mfma_f32_32x32x16_bf16 v[16:31], v[132:135], v[204:207], v[16:31]
	v_mfma_f32_32x32x16_bf16 v[16:31], v[140:143], v[232:235], v[16:31]
	s_cbranch_scc1 .LBB0_914
	v_mov_b32_e32 v232, v144
	s_cmp_eq_u32 s22, 0x7e0000
	s_mov_b64 s[4:5], -1
	s_cbranch_scc1 .LBB0_903
